# attention row-max cross-half exchange via v_permlane32_swap instead of ds_bpermute + lgkmcnt(0) wait
# speedup vs baseline: 1.0053x; 1.0053x over previous
.LBB0_496:
	v_max3_f32 v1, v0, v128, v112
	v_cmp_lt_i32_e32 vcc, v228, v222
	v_max3_f32 v1, v1, v129, v113
	v_max3_f32 v1, v1, v130, v114
	v_max3_f32 v1, v1, v131, v115
	v_cndmask_b32_e32 v10, v221, v228, vcc
	v_max3_f32 v1, v1, v132, v116
	v_lshlrev_b32_e32 v243, 2, v10
	v_max3_f32 v1, v1, v133, v117
	v_max3_f32 v1, v1, v134, v118
	v_max3_f32 v1, v1, v135, v119
	v_max3_f32 v1, v1, v136, v120
	v_max3_f32 v1, v1, v137, v121
	v_max3_f32 v1, v1, v138, v122
	v_max3_f32 v1, v1, v139, v123
	v_max3_f32 v1, v1, v140, v124
	v_max3_f32 v1, v1, v141, v125
	v_max3_f32 v1, v1, v142, v126
	v_max3_f32 v1, v1, v143, v127
	v_mov_b32_e32 v10, v1
	s_nop 1
	v_permlane32_swap_b32_e32 v10, v1
	v_max3_f32 v1, v1, v1, v10
	v_cmp_lt_f32_e32 vcc, s33, v1
	s_cbranch_vccz .LBB0_498
	v_exp_f32_e64 v10, -v1
	v_add_f32_e32 v197, v197, v1
	v_pk_add_f32 v[142:143], v[142:143], v[0:1] op_sel:[0,1] op_sel_hi:[1,1] neg_lo:[0,1] neg_hi:[0,1]
	v_pk_add_f32 v[140:141], v[140:141], v[0:1] op_sel:[0,1] op_sel_hi:[1,1] neg_lo:[0,1] neg_hi:[0,1]
	v_pk_add_f32 v[138:139], v[138:139], v[0:1] op_sel:[0,1] op_sel_hi:[1,1] neg_lo:[0,1] neg_hi:[0,1]
	v_pk_add_f32 v[136:137], v[136:137], v[0:1] op_sel:[0,1] op_sel_hi:[1,1] neg_lo:[0,1] neg_hi:[0,1]
	v_pk_add_f32 v[134:135], v[134:135], v[0:1] op_sel:[0,1] op_sel_hi:[1,1] neg_lo:[0,1] neg_hi:[0,1]
	v_pk_add_f32 v[132:133], v[132:133], v[0:1] op_sel:[0,1] op_sel_hi:[1,1] neg_lo:[0,1] neg_hi:[0,1]
	v_pk_add_f32 v[130:131], v[130:131], v[0:1] op_sel:[0,1] op_sel_hi:[1,1] neg_lo:[0,1] neg_hi:[0,1]
	v_pk_add_f32 v[128:129], v[128:129], v[0:1] op_sel:[0,1] op_sel_hi:[1,1] neg_lo:[0,1] neg_hi:[0,1]
	v_pk_mul_f32 v[78:79], v[78:79], v[10:11] op_sel_hi:[1,0]
	v_pk_mul_f32 v[76:77], v[76:77], v[10:11] op_sel_hi:[1,0]
	v_pk_mul_f32 v[74:75], v[74:75], v[10:11] op_sel_hi:[1,0]
	v_pk_mul_f32 v[72:73], v[72:73], v[10:11] op_sel_hi:[1,0]
	v_pk_mul_f32 v[70:71], v[70:71], v[10:11] op_sel_hi:[1,0]
	v_pk_mul_f32 v[68:69], v[68:69], v[10:11] op_sel_hi:[1,0]
	v_pk_mul_f32 v[66:67], v[66:67], v[10:11] op_sel_hi:[1,0]
	v_pk_mul_f32 v[64:65], v[64:65], v[10:11] op_sel_hi:[1,0]
	v_pk_mul_f32 v[62:63], v[62:63], v[10:11] op_sel_hi:[1,0]
	v_pk_mul_f32 v[60:61], v[60:61], v[10:11] op_sel_hi:[1,0]
	v_pk_mul_f32 v[58:59], v[58:59], v[10:11] op_sel_hi:[1,0]
	v_pk_mul_f32 v[56:57], v[56:57], v[10:11] op_sel_hi:[1,0]
	v_pk_mul_f32 v[54:55], v[54:55], v[10:11] op_sel_hi:[1,0]
	v_pk_mul_f32 v[52:53], v[52:53], v[10:11] op_sel_hi:[1,0]
	v_pk_mul_f32 v[50:51], v[50:51], v[10:11] op_sel_hi:[1,0]
	v_pk_mul_f32 v[48:49], v[48:49], v[10:11] op_sel_hi:[1,0]
	v_mul_f32_e32 v241, v241, v10
	v_pk_add_f32 v[126:127], v[126:127], v[0:1] op_sel:[0,1] op_sel_hi:[1,1] neg_lo:[0,1] neg_hi:[0,1]
	v_pk_add_f32 v[124:125], v[124:125], v[0:1] op_sel:[0,1] op_sel_hi:[1,1] neg_lo:[0,1] neg_hi:[0,1]
	v_pk_add_f32 v[122:123], v[122:123], v[0:1] op_sel:[0,1] op_sel_hi:[1,1] neg_lo:[0,1] neg_hi:[0,1]
	v_pk_add_f32 v[120:121], v[120:121], v[0:1] op_sel:[0,1] op_sel_hi:[1,1] neg_lo:[0,1] neg_hi:[0,1]
	v_pk_add_f32 v[118:119], v[118:119], v[0:1] op_sel:[0,1] op_sel_hi:[1,1] neg_lo:[0,1] neg_hi:[0,1]
	v_pk_add_f32 v[116:117], v[116:117], v[0:1] op_sel:[0,1] op_sel_hi:[1,1] neg_lo:[0,1] neg_hi:[0,1]
	v_pk_add_f32 v[114:115], v[114:115], v[0:1] op_sel:[0,1] op_sel_hi:[1,1] neg_lo:[0,1] neg_hi:[0,1]
	v_pk_add_f32 v[112:113], v[112:113], v[0:1] op_sel:[0,1] op_sel_hi:[1,1] neg_lo:[0,1] neg_hi:[0,1]

.LBB0_500:
	v_max3_f32 v127, v0, v96, v80
	v_max3_f32 v127, v127, v97, v81
	v_max3_f32 v127, v127, v98, v82
	v_max3_f32 v127, v127, v99, v83
	v_max3_f32 v127, v127, v100, v84
	v_max3_f32 v127, v127, v101, v85
	v_max3_f32 v127, v127, v102, v86
	v_max3_f32 v127, v127, v103, v87
	v_max3_f32 v127, v127, v104, v88
	v_max3_f32 v127, v127, v105, v89
	v_max3_f32 v127, v127, v106, v90
	v_max3_f32 v127, v127, v107, v91
	v_max3_f32 v127, v127, v108, v92
	v_max3_f32 v127, v127, v109, v93
	v_max3_f32 v127, v127, v110, v94
	v_max3_f32 v127, v127, v111, v95
	v_mov_b32_e32 v136, v127
	s_nop 1
	v_permlane32_swap_b32_e32 v136, v127
	v_max3_f32 v127, v127, v127, v136
	v_cmp_lt_f32_e32 vcc, s33, v127
	s_cbranch_vccz .LBB0_502
	v_exp_f32_e64 v136, -v127
	v_add_f32_e32 v239, v239, v127
	v_pk_add_f32 v[110:111], v[110:111], v[126:127] op_sel:[0,1] op_sel_hi:[1,1] neg_lo:[0,1] neg_hi:[0,1]
	v_pk_add_f32 v[108:109], v[108:109], v[126:127] op_sel:[0,1] op_sel_hi:[1,1] neg_lo:[0,1] neg_hi:[0,1]
	v_pk_add_f32 v[106:107], v[106:107], v[126:127] op_sel:[0,1] op_sel_hi:[1,1] neg_lo:[0,1] neg_hi:[0,1]
	v_pk_add_f32 v[104:105], v[104:105], v[126:127] op_sel:[0,1] op_sel_hi:[1,1] neg_lo:[0,1] neg_hi:[0,1]
	v_pk_add_f32 v[102:103], v[102:103], v[126:127] op_sel:[0,1] op_sel_hi:[1,1] neg_lo:[0,1] neg_hi:[0,1]
	v_pk_add_f32 v[100:101], v[100:101], v[126:127] op_sel:[0,1] op_sel_hi:[1,1] neg_lo:[0,1] neg_hi:[0,1]
	v_pk_add_f32 v[98:99], v[98:99], v[126:127] op_sel:[0,1] op_sel_hi:[1,1] neg_lo:[0,1] neg_hi:[0,1]
	v_pk_add_f32 v[96:97], v[96:97], v[126:127] op_sel:[0,1] op_sel_hi:[1,1] neg_lo:[0,1] neg_hi:[0,1]
	v_pk_mul_f32 v[46:47], v[46:47], v[136:137] op_sel_hi:[1,0]
	v_pk_mul_f32 v[44:45], v[44:45], v[136:137] op_sel_hi:[1,0]
	v_pk_mul_f32 v[42:43], v[42:43], v[136:137] op_sel_hi:[1,0]
	v_pk_mul_f32 v[40:41], v[40:41], v[136:137] op_sel_hi:[1,0]
	v_pk_mul_f32 v[38:39], v[38:39], v[136:137] op_sel_hi:[1,0]
	v_pk_mul_f32 v[36:37], v[36:37], v[136:137] op_sel_hi:[1,0]
	v_pk_mul_f32 v[34:35], v[34:35], v[136:137] op_sel_hi:[1,0]
	v_pk_mul_f32 v[32:33], v[32:33], v[136:137] op_sel_hi:[1,0]
	v_pk_mul_f32 v[30:31], v[30:31], v[136:137] op_sel_hi:[1,0]
	v_pk_mul_f32 v[28:29], v[28:29], v[136:137] op_sel_hi:[1,0]
	v_pk_mul_f32 v[26:27], v[26:27], v[136:137] op_sel_hi:[1,0]
	v_pk_mul_f32 v[24:25], v[24:25], v[136:137] op_sel_hi:[1,0]
	v_pk_mul_f32 v[22:23], v[22:23], v[136:137] op_sel_hi:[1,0]
	v_pk_mul_f32 v[20:21], v[20:21], v[136:137] op_sel_hi:[1,0]
	v_pk_mul_f32 v[18:19], v[18:19], v[136:137] op_sel_hi:[1,0]
	v_pk_mul_f32 v[16:17], v[16:17], v[136:137] op_sel_hi:[1,0]
	v_mul_f32_e32 v238, v238, v136
	v_pk_add_f32 v[94:95], v[94:95], v[126:127] op_sel:[0,1] op_sel_hi:[1,1] neg_lo:[0,1] neg_hi:[0,1]
	v_pk_add_f32 v[92:93], v[92:93], v[126:127] op_sel:[0,1] op_sel_hi:[1,1] neg_lo:[0,1] neg_hi:[0,1]
	v_pk_add_f32 v[90:91], v[90:91], v[126:127] op_sel:[0,1] op_sel_hi:[1,1] neg_lo:[0,1] neg_hi:[0,1]
	v_pk_add_f32 v[88:89], v[88:89], v[126:127] op_sel:[0,1] op_sel_hi:[1,1] neg_lo:[0,1] neg_hi:[0,1]
	v_pk_add_f32 v[86:87], v[86:87], v[126:127] op_sel:[0,1] op_sel_hi:[1,1] neg_lo:[0,1] neg_hi:[0,1]
	v_pk_add_f32 v[84:85], v[84:85], v[126:127] op_sel:[0,1] op_sel_hi:[1,1] neg_lo:[0,1] neg_hi:[0,1]
	v_pk_add_f32 v[82:83], v[82:83], v[126:127] op_sel:[0,1] op_sel_hi:[1,1] neg_lo:[0,1] neg_hi:[0,1]
	v_pk_add_f32 v[80:81], v[80:81], v[126:127] op_sel:[0,1] op_sel_hi:[1,1] neg_lo:[0,1] neg_hi:[0,1]
